# ssm pass1: u fragment prefetched two groups ahead (parity-selected register sets), on top of pass2 identity-MFMA change
# baseline (speedup 1.0000x reference)
; #define LAS __attribute__((address_space(3)))
; __device__ __forceinline__ void ssm_bu_tile(const SsmOps& S, bf16x8 uh, LAS float* tile, int lane) {
;     const int fr = lane & 15, fq = lane >> 4;
;     if (fq >= 2) uh = (bf16x8){0, 0, 0, 0, 0, 0, 0, 0};
; #pragma unroll
;     for (int nb = 0; nb < 8; ++nb) { f32x4 acc = {0.f, 0.f, 0.f, 0.f};
;         acc = __builtin_amdgcn_mfma_f32_16x16x32_bf16(S.bh[nb], uh, acc, 0, 0, 0);
;         *(LAS f32x4*)(tile + fr * TSTR + 16 * nb + 4 * fq) = acc; }
; __device__ __forceinline__ void ssm_pass1(LAS unsigned char* lds, const bf16_t* US, float* SST, const float* ABAR, const bf16_t* BBH, const bf16_t* BBL, int gw, int NGW, int lane, int wave) {
;     LAS float* tile = (LAS float*)(lds + 32768 + wave * (16 * TSTR * 4));
;     for (int idx = gw; idx < NB * NG * 7; idx += NGW) {
;         const int c = idx % 7, bg = idx / 7, b = bg >> 5, g = bg & 31;
;         SsmOps S; ssm_ops_load(S, ABAR, BBH, BBL, g, lane);
;         float xr = 0.f, xi = 0.f; const int tokc = b * SEQ + c * 256;
;         bf16x8 uh; ssm_u_load(uh, US, tokc, g, lane);
;         for (int grp = 0; grp < 16; ++grp) {
;             ssm_bu_tile(S, uh, tile, lane);
;             if (grp < 15) ssm_u_load(uh, US, tokc + (grp + 1) * 16, g, lane);
.LBB0_485:
	s_cmpk_gt_i32 s92, 0xdff
	s_cbranch_scc1 .LBB0_490
	s_add_u32 s0, s28, 0x100000
	s_addc_u32 s1, s29, 0
	v_readlane_b32 s3, v249, 18
	s_add_u32 s10, s28, 0x110000
	s_mulk_i32 s3, 0x2100
	v_and_b32_e32 v48, 15, v197
	s_addc_u32 s11, s29, 0
	s_add_i32 s3, s3, 0
	v_lshrrev_b32_e32 v0, 1, v197
	v_mul_u32_u24_e32 v3, 0x210, v48
	v_and_b32_e32 v4, 48, v197
	v_and_b32_e32 v0, 8, v0
	s_waitcnt lgkmcnt(0)
	v_lshlrev_b32_e32 v1, 4, v197
	v_add3_u32 v49, s3, v3, v4
	v_lshl_add_u32 v50, v196, 2, s3
	s_movk_i32 s3, 0xf0
	v_lshlrev_b32_e32 v2, 1, v196
	v_mov_b32_e32 v37, 0
	v_lshlrev_b32_e32 v36, 1, v0
	v_and_or_b32 v1, v1, s3, v0
	s_mov_b32 s13, 0
	v_cmp_gt_u32_e32 vcc, 32, v196
	v_cmp_lt_u32_e64 s[4:5], 31, v196
	v_lshl_add_u64 v[38:39], s[46:47], 0, v[36:37]
	v_or_b32_e32 v51, 16, v48
	v_lshlrev_b32_e32 v52, 1, v1
	v_lshlrev_b32_e32 v53, 2, v2
	v_lshlrev_b32_e32 v36, 1, v0
	v_lshlrev_b32_e32 v54, 2, v196
	s_mov_b32 s3, s92
	s_mov_b32 s98, 0x4000
	s_mov_b32 s99, 0
.LBB0_487:
	s_mul_hi_i32 s12, s3, 0x92492493
	s_add_i32 s12, s12, s3
	s_lshr_b32 s14, s12, 31
	s_ashr_i32 s12, s12, 2
	s_add_i32 s14, s12, s14
	s_mul_i32 s15, s14, 7
	s_lshl_b32 s17, s14, 6
	s_sub_i32 s16, s3, s15
	s_and_b32 s12, s14, 31
	s_and_b32 s15, s17, 0xfffff800
	s_lshl_b32 s17, s16, 8
	v_lshl_or_b32 v0, s12, 12, v52
	v_lshl_or_b32 v1, s12, 9, v53
	s_add_i32 s17, s15, s17
	global_load_dwordx2 v[40:41], v1, s[0:1]
	global_load_dwordx4 v[4:7], v0, s[10:11]
	global_load_dwordx4 v[8:11], v0, s[10:11] offset:512
	global_load_dwordx4 v[12:15], v0, s[10:11] offset:1024
	global_load_dwordx4 v[16:19], v0, s[10:11] offset:1536
	global_load_dwordx4 v[20:23], v0, s[10:11] offset:2048
	global_load_dwordx4 v[24:27], v0, s[10:11] offset:2560
	global_load_dwordx4 v[56:59], v0, s[10:11] offset:3072
	global_load_dwordx4 v[60:63], v0, s[10:11] offset:3584
	v_or_b32_e32 v0, s17, v48
	v_ashrrev_i32_e32 v1, 31, v0
	v_lshlrev_b64 v[0:1], 10, v[0:1]
	s_lshl_b32 s12, s12, 5
	v_lshl_add_u64 v[0:1], s[46:47], 0, v[0:1]
	v_lshl_add_u64 v[0:1], v[0:1], 0, s[12:13]
	v_lshl_add_u64 v[0:1], v[0:1], 0, v[36:37]
	global_load_dwordx4 v[112:115], v[0:1], off
	v_lshl_add_u64 v[120:121], v[0:1], 0, s[98:99]
	global_load_dwordx4 v[116:119], v[120:121], off
	v_lshl_add_u64 v[42:43], v[38:39], 0, s[12:13]
	s_lshl_b32 s12, s3, 8
	s_add_i32 s12, s12, s15
	v_or_b32_e32 v46, s12, v51
	s_mul_i32 s12, s14, 0x700
	v_subrev_u32_e32 v55, s12, v46
	s_mov_b32 s12, 0
	v_mov_b32_e32 v46, 0
	v_mov_b32_e32 v47, v37
	s_waitcnt vmcnt(0)
	v_pk_mov_b32 v[44:45], v[40:41], v[40:41] op_sel:[1,0]
	v_cndmask_b32_e32 v7, 0, v7, vcc
	v_cndmask_b32_e32 v6, 0, v6, vcc
	v_cndmask_b32_e32 v5, 0, v5, vcc
	v_cndmask_b32_e32 v4, 0, v4, vcc
	v_cndmask_b32_e32 v11, 0, v11, vcc
	v_cndmask_b32_e32 v10, 0, v10, vcc
	v_cndmask_b32_e32 v9, 0, v9, vcc
	v_cndmask_b32_e32 v8, 0, v8, vcc
	v_cndmask_b32_e32 v15, 0, v15, vcc
	v_cndmask_b32_e32 v14, 0, v14, vcc
	v_cndmask_b32_e32 v13, 0, v13, vcc
	v_cndmask_b32_e32 v12, 0, v12, vcc
	v_cndmask_b32_e32 v19, 0, v19, vcc
	v_cndmask_b32_e32 v18, 0, v18, vcc
	v_cndmask_b32_e32 v17, 0, v17, vcc
	v_cndmask_b32_e32 v16, 0, v16, vcc
	v_cndmask_b32_e32 v31, 0, v23, vcc
	v_cndmask_b32_e32 v30, 0, v22, vcc
	v_cndmask_b32_e32 v29, 0, v21, vcc
	v_cndmask_b32_e32 v28, 0, v20, vcc
	v_cndmask_b32_e32 v35, 0, v27, vcc
	v_cndmask_b32_e32 v34, 0, v26, vcc
	v_cndmask_b32_e32 v33, 0, v25, vcc
	v_cndmask_b32_e32 v32, 0, v24, vcc
	v_cndmask_b32_e32 v27, 0, v59, vcc
	v_cndmask_b32_e32 v26, 0, v58, vcc
	v_cndmask_b32_e32 v25, 0, v57, vcc
	v_cndmask_b32_e32 v24, 0, v56, vcc
	v_cndmask_b32_e32 v23, 0, v63, vcc
	v_cndmask_b32_e32 v22, 0, v62, vcc
	v_cndmask_b32_e32 v21, 0, v61, vcc
	v_cndmask_b32_e32 v20, 0, v60, vcc
.LBB0_488:
	s_waitcnt vmcnt(1)
	s_bitcmp1_b32 s12, 4
	s_cselect_b64 s[100:101], -1, 0
	s_nop 0
	v_cndmask_b32_e64 v3, v115, v119, s[100:101]
	v_cndmask_b32_e64 v2, v114, v118, s[100:101]
	v_cndmask_b32_e64 v1, v113, v117, s[100:101]
	v_cndmask_b32_e64 v0, v112, v116, s[100:101]
	v_cndmask_b32_e64 v3, v3, 0, s[4:5]
	v_cndmask_b32_e64 v2, v2, 0, s[4:5]
	v_cndmask_b32_e64 v1, v1, 0, s[4:5]
	v_cndmask_b32_e64 v0, v0, 0, s[4:5]
	v_pk_mul_f32 v[104:105], v[40:41], v[46:47]
	v_pk_mul_f32 v[46:47], v[44:45], v[46:47]
	v_mfma_f32_16x16x32_bf16 v[56:59], v[4:7], v[0:3], 0
	v_add_f32_e32 v46, v46, v47
	v_mfma_f32_16x16x32_bf16 v[60:63], v[8:11], v[0:3], 0
	v_mfma_f32_16x16x32_bf16 v[64:67], v[12:15], v[0:3], 0
	s_nop 4
	ds_write_b128 v49, v[56:59] offset:32768
	v_mfma_f32_16x16x32_bf16 v[68:71], v[16:19], v[0:3], 0
	ds_write_b128 v49, v[60:63] offset:32832
	ds_write_b128 v49, v[64:67] offset:32896
	s_nop 5
	ds_write_b128 v49, v[68:71] offset:32960
	v_sub_f32_e32 v71, v104, v105
	v_mfma_f32_16x16x32_bf16 v[72:75], v[28:31], v[0:3], 0
	v_add_u32_e32 v64, 0x90, v50
	v_add_u32_e32 v65, 0xa0, v50
	v_add_u32_e32 v66, 0xb0, v50
	v_mfma_f32_16x16x32_bf16 v[56:59], v[32:35], v[0:3], 0
	v_add_u32_e32 v67, 0xc0, v50
	v_add_u32_e32 v68, 0xd0, v50
	v_add_u32_e32 v69, 0xe0, v50
	v_mfma_f32_16x16x32_bf16 v[60:63], v[24:27], v[0:3], 0
	ds_write_b128 v49, v[72:75] offset:33024
	s_nop 2
	ds_write_b128 v49, v[56:59] offset:33088
	s_nop 2
	ds_write_b128 v49, v[60:63] offset:33152
	v_add_u32_e32 v56, 16, v50
	v_mfma_f32_16x16x32_bf16 v[0:3], v[20:23], v[0:3], 0
	v_add_u32_e32 v57, 32, v50
	v_add_u32_e32 v58, 48, v50
	v_add_u32_e32 v59, 64, v50
	v_add_u32_e32 v60, 0x50, v50
	v_add_u32_e32 v61, 0x60, v50
	s_nop 2
	ds_write_b128 v49, v[0:3] offset:33216
	v_add_u32_e32 v0, s12, v55
	v_add_u32_e32 v0, 16, v0
	v_ashrrev_i32_e32 v1, 31, v0
	v_lshlrev_b64 v[0:1], 10, v[0:1]
	s_waitcnt lgkmcnt(0)
	v_lshl_add_u64 v[0:1], v[42:43], 0, v[0:1]
	s_bitcmp1_b32 s12, 4
	s_cbranch_scc1 .Lssm1_ld_odd
	global_load_dwordx4 v[112:115], v[0:1], off
	s_branch .Lssm1_ld_done
; __device__ __forceinline__ void ssm_pass1(LAS unsigned char* lds, const bf16_t* US, float* SST, const float* ABAR, const bf16_t* BBH, const bf16_t* BBL, int gw, int NGW, int lane, int wave) {
;     ...
;         for (int grp = 0; grp < 16; ++grp) {
;             ssm_bu_tile(S, uh, tile, lane);
;             if (grp < 15) ssm_u_load(uh, US, tokc + (grp + 1) * 16, g, lane);
;             float br[16], bi[16];
; #pragma unroll
;             for (int t = 0; t < 16; ++t) { br[t] = tile[t * TSTR + lane]; bi[t] = tile[t * TSTR + 64 + lane]; }
;             asm volatile("s_waitcnt lgkmcnt(0)" ::: "memory");
; #pragma unroll
;             for (int t = 0; t < 16; ++t) { const float nr = S.ar * xr - S.ai * xi + br[t], ni = S.ar * xi + S.ai * xr + bi[t]; xr = nr; xi = ni; }
.Lssm1_ld_odd:
	global_load_dwordx4 v[116:119], v[0:1], off
.Lssm1_ld_done:
	ds_read2st64_b32 v[72:73], v50 offset0:128 offset1:129
	ds_read2st64_b32 v[74:75], v56 offset0:130 offset1:131
	ds_read2st64_b32 v[76:77], v57 offset0:132 offset1:133
	ds_read2st64_b32 v[78:79], v58 offset0:134 offset1:135
	ds_read2st64_b32 v[80:81], v59 offset0:136 offset1:137
	s_waitcnt lgkmcnt(4)
	v_add_f32_e32 v46, v46, v73
	v_add_f32_e32 v72, v71, v72
	v_pk_mul_f32 v[46:47], v[44:45], v[46:47] op_sel_hi:[1,0]
	ds_read2st64_b32 v[82:83], v60 offset0:138 offset1:139
	v_pk_fma_f32 v[104:105], v[40:41], v[72:73], v[46:47] neg_lo:[0,0,1] neg_hi:[0,0,1]
	v_pk_fma_f32 v[46:47], v[40:41], v[72:73], v[46:47] op_sel_hi:[1,0,1]
	ds_read2st64_b32 v[84:85], v61 offset0:140 offset1:141
	v_mov_b32_e32 v105, v47
	s_waitcnt lgkmcnt(5)
	v_pk_add_f32 v[46:47], v[74:75], v[104:105]
	v_add_u32_e32 v62, 0x70, v50
	v_pk_mul_f32 v[72:73], v[40:41], v[46:47]
	v_pk_mul_f32 v[46:47], v[40:41], v[46:47] op_sel:[0,1] op_sel_hi:[1,0]
	v_sub_f32_e32 v71, v72, v73
	v_add_f32_e32 v46, v46, v47
	s_waitcnt lgkmcnt(4)
	v_add_f32_e32 v46, v77, v46
	v_add_f32_e32 v72, v76, v71
	v_pk_mul_f32 v[46:47], v[44:45], v[46:47] op_sel_hi:[1,0]
	ds_read2st64_b32 v[86:87], v62 offset0:142 offset1:143
	v_pk_fma_f32 v[74:75], v[40:41], v[72:73], v[46:47] neg_lo:[0,0,1] neg_hi:[0,0,1]
	v_pk_fma_f32 v[46:47], v[40:41], v[72:73], v[46:47] op_sel_hi:[1,0,1]
	v_add_u32_e32 v63, 0x80, v50
	v_mov_b32_e32 v75, v47
	s_waitcnt lgkmcnt(4)
	v_pk_add_f32 v[46:47], v[78:79], v[74:75]
	ds_read2st64_b32 v[88:89], v63 offset0:144 offset1:145
	v_pk_mul_f32 v[72:73], v[40:41], v[46:47]
	v_pk_mul_f32 v[46:47], v[40:41], v[46:47] op_sel:[0,1] op_sel_hi:[1,0]
	v_sub_f32_e32 v71, v72, v73
	v_add_f32_e32 v46, v46, v47
	s_waitcnt lgkmcnt(4)
	v_add_f32_e32 v46, v81, v46
	v_add_f32_e32 v72, v80, v71
	v_pk_mul_f32 v[46:47], v[44:45], v[46:47] op_sel_hi:[1,0]
	ds_read2st64_b32 v[90:91], v64 offset0:146 offset1:147
	v_pk_fma_f32 v[74:75], v[40:41], v[72:73], v[46:47] neg_lo:[0,0,1] neg_hi:[0,0,1]
	v_pk_fma_f32 v[46:47], v[40:41], v[72:73], v[46:47] op_sel_hi:[1,0,1]
	ds_read2st64_b32 v[92:93], v65 offset0:148 offset1:149
	v_mov_b32_e32 v75, v47
	s_waitcnt lgkmcnt(5)
	v_pk_add_f32 v[46:47], v[82:83], v[74:75]
	ds_read2st64_b32 v[94:95], v66 offset0:150 offset1:151
	v_pk_mul_f32 v[72:73], v[40:41], v[46:47]
	v_pk_mul_f32 v[46:47], v[40:41], v[46:47] op_sel:[0,1] op_sel_hi:[1,0]
	v_sub_f32_e32 v71, v72, v73
	v_add_f32_e32 v46, v46, v47
	s_waitcnt lgkmcnt(5)
	v_add_f32_e32 v46, v85, v46
	v_add_f32_e32 v72, v84, v71
	v_pk_mul_f32 v[46:47], v[44:45], v[46:47] op_sel_hi:[1,0]
	ds_read2st64_b32 v[96:97], v67 offset0:152 offset1:153
	v_pk_fma_f32 v[74:75], v[40:41], v[72:73], v[46:47] neg_lo:[0,0,1] neg_hi:[0,0,1]
	v_pk_fma_f32 v[46:47], v[40:41], v[72:73], v[46:47] op_sel_hi:[1,0,1]
	ds_read2st64_b32 v[98:99], v68 offset0:154 offset1:155
	v_mov_b32_e32 v75, v47
	s_waitcnt lgkmcnt(6)
	v_pk_add_f32 v[46:47], v[86:87], v[74:75]
	ds_read2st64_b32 v[100:101], v69 offset0:156 offset1:157
	v_pk_mul_f32 v[72:73], v[40:41], v[46:47]
	v_pk_mul_f32 v[46:47], v[40:41], v[46:47] op_sel:[0,1] op_sel_hi:[1,0]
	v_sub_f32_e32 v71, v72, v73
	v_add_f32_e32 v46, v46, v47
	s_waitcnt lgkmcnt(6)
	v_add_f32_e32 v46, v89, v46
	v_add_f32_e32 v72, v88, v71
	v_pk_mul_f32 v[46:47], v[44:45], v[46:47] op_sel_hi:[1,0]
	v_add_u32_e32 v70, 0xf0, v50
	v_pk_fma_f32 v[74:75], v[40:41], v[72:73], v[46:47] neg_lo:[0,0,1] neg_hi:[0,0,1]
	v_pk_fma_f32 v[46:47], v[40:41], v[72:73], v[46:47] op_sel_hi:[1,0,1]
	ds_read2st64_b32 v[102:103], v70 offset0:158 offset1:159
	v_mov_b32_e32 v75, v47
	s_waitcnt lgkmcnt(6)
	v_pk_add_f32 v[46:47], v[90:91], v[74:75]
	s_waitcnt lgkmcnt(0)
	s_add_i32 s12, s12, 16
	v_pk_mul_f32 v[72:73], v[40:41], v[46:47]
	v_pk_mul_f32 v[46:47], v[40:41], v[46:47] op_sel:[0,1] op_sel_hi:[1,0]
	v_sub_f32_e32 v71, v72, v73
	v_add_f32_e32 v46, v46, v47
	s_waitcnt lgkmcnt(5)
	v_add_f32_e32 v46, v93, v46
	v_add_f32_e32 v72, v92, v71
	v_pk_mul_f32 v[46:47], v[44:45], v[46:47] op_sel_hi:[1,0]
	s_cmpk_eq_i32 s12, 0xf0
	v_pk_fma_f32 v[74:75], v[40:41], v[72:73], v[46:47] neg_lo:[0,0,1] neg_hi:[0,0,1]
	v_pk_fma_f32 v[46:47], v[40:41], v[72:73], v[46:47] op_sel_hi:[1,0,1]
	s_nop 0
	v_mov_b32_e32 v75, v47
	s_waitcnt lgkmcnt(4)
	v_pk_add_f32 v[46:47], v[94:95], v[74:75]
	s_nop 0
	v_pk_mul_f32 v[72:73], v[40:41], v[46:47]
	v_pk_mul_f32 v[46:47], v[40:41], v[46:47] op_sel:[0,1] op_sel_hi:[1,0]
	v_sub_f32_e32 v71, v72, v73
	v_add_f32_e32 v46, v46, v47
	s_waitcnt lgkmcnt(3)
	v_add_f32_e32 v46, v97, v46
	v_add_f32_e32 v72, v96, v71
	v_pk_mul_f32 v[46:47], v[44:45], v[46:47] op_sel_hi:[1,0]
	s_nop 0
	v_pk_fma_f32 v[74:75], v[40:41], v[72:73], v[46:47] neg_lo:[0,0,1] neg_hi:[0,0,1]
	v_pk_fma_f32 v[46:47], v[40:41], v[72:73], v[46:47] op_sel_hi:[1,0,1]
	s_nop 0
	v_mov_b32_e32 v75, v47
	s_waitcnt lgkmcnt(2)
	v_pk_add_f32 v[46:47], v[98:99], v[74:75]
	s_nop 0
	v_pk_mul_f32 v[72:73], v[40:41], v[46:47]
	v_pk_mul_f32 v[46:47], v[40:41], v[46:47] op_sel:[0,1] op_sel_hi:[1,0]
	v_sub_f32_e32 v71, v72, v73
	v_add_f32_e32 v46, v46, v47
	s_waitcnt lgkmcnt(1)
	v_add_f32_e32 v46, v101, v46
	v_add_f32_e32 v72, v100, v71
	v_pk_mul_f32 v[46:47], v[44:45], v[46:47] op_sel_hi:[1,0]
	s_nop 0
	v_pk_fma_f32 v[74:75], v[40:41], v[72:73], v[46:47] neg_lo:[0,0,1] neg_hi:[0,0,1]
	v_pk_fma_f32 v[46:47], v[40:41], v[72:73], v[46:47] op_sel_hi:[1,0,1]
	s_nop 0
	v_mov_b32_e32 v75, v47
	s_waitcnt lgkmcnt(0)
	v_pk_add_f32 v[46:47], v[102:103], v[74:75]
	s_cbranch_scc0 .LBB0_488
; __device__ __forceinline__ void ssm_pass1(LAS unsigned char* lds, const bf16_t* US, float* SST, const float* ABAR, const bf16_t* BBH, const bf16_t* BBL, int gw, int NGW, int lane, int wave) {
;     ...
;             ssm_bu_tile(S, uh, tile, lane);
;             if (grp < 15) ssm_u_load(uh, US, tokc + (grp + 1) * 16, g, lane);
;             float br[16], bi[16];
; #pragma unroll
;             for (int t = 0; t < 16; ++t) { br[t] = tile[t * TSTR + lane]; bi[t] = tile[t * TSTR + 64 + lane]; }
;             asm volatile("s_waitcnt lgkmcnt(0)" ::: "memory");
; #pragma unroll
;             for (int t = 0; t < 16; ++t) { const float nr = S.ar * xr - S.ai * xi + br[t], ni = S.ar * xi + S.ai * xr + bi[t]; xr = nr; xi = ni; }
;         }
;         float* so = SST + ((size_t)bg * 8 + c) * 128; so[lane] = xr; so[64 + lane] = xi;
	s_waitcnt vmcnt(0)
	v_cndmask_b32_e64 v3, v119, 0, s[4:5]
	v_cndmask_b32_e64 v2, v118, 0, s[4:5]
	v_cndmask_b32_e64 v1, v117, 0, s[4:5]
	v_cndmask_b32_e64 v0, v116, 0, s[4:5]
	s_ashr_i32 s15, s14, 31
	s_ashr_i32 s17, s16, 31
	v_mfma_f32_16x16x32_bf16 v[4:7], v[4:7], v[0:3], 0
	s_lshl_b64 s[14:15], s[14:15], 12
	s_add_u32 s12, s6, s14
	s_addc_u32 s18, s7, s15
	v_mfma_f32_16x16x32_bf16 v[8:11], v[8:11], v[0:3], 0
	s_lshl_b64 s[14:15], s[16:17], 9
	s_nop 2
	ds_write_b128 v49, v[4:7] offset:32768
	s_add_u32 s14, s12, s14
	v_mfma_f32_16x16x32_bf16 v[12:15], v[12:15], v[0:3], 0
	s_addc_u32 s15, s18, s15
	s_add_i32 s3, s3, s33
	s_cmpk_gt_i32 s3, 0xdff
	v_mfma_f32_16x16x32_bf16 v[16:19], v[16:19], v[0:3], 0
	ds_write_b128 v49, v[8:11] offset:32832
	s_nop 2
	ds_write_b128 v49, v[12:15] offset:32896
	s_nop 2
	ds_write_b128 v49, v[16:19] offset:32960
	v_mfma_f32_16x16x32_bf16 v[28:31], v[28:31], v[0:3], 0
	v_mfma_f32_16x16x32_bf16 v[4:7], v[32:35], v[0:3], 0
	v_mul_f32_e64 v32, v40, v46
	v_mul_f32_e64 v33, v41, v47
	v_sub_f32_e32 v32, v32, v33
	v_mfma_f32_16x16x32_bf16 v[8:11], v[24:27], v[0:3], 0
	s_nop 2
	ds_write_b128 v49, v[28:31] offset:33024
	ds_write_b128 v49, v[4:7] offset:33088
	s_nop 2
	ds_write_b128 v49, v[8:11] offset:33152
	v_mfma_f32_16x16x32_bf16 v[0:3], v[20:23], v[0:3], 0
	s_nop 7
	ds_write_b128 v49, v[0:3] offset:33216
	s_waitcnt lgkmcnt(0)
	ds_read2st64_b32 v[0:1], v50 offset0:128 offset1:129
	ds_read2st64_b32 v[2:3], v56 offset0:130 offset1:131
	ds_read2st64_b32 v[4:5], v57 offset0:132 offset1:133
	ds_read2st64_b32 v[6:7], v58 offset0:134 offset1:135
	ds_read2st64_b32 v[8:9], v59 offset0:136 offset1:137
	ds_read2st64_b32 v[10:11], v60 offset0:138 offset1:139
	ds_read2st64_b32 v[12:13], v61 offset0:140 offset1:141
	ds_read2st64_b32 v[14:15], v62 offset0:142 offset1:143
	ds_read2st64_b32 v[16:17], v63 offset0:144 offset1:145
	ds_read2st64_b32 v[18:19], v64 offset0:146 offset1:147
	ds_read2st64_b32 v[20:21], v65 offset0:148 offset1:149
	ds_read2st64_b32 v[22:23], v66 offset0:150 offset1:151
	ds_read2st64_b32 v[24:25], v67 offset0:152 offset1:153
	ds_read2st64_b32 v[26:27], v68 offset0:154 offset1:155
	ds_read2st64_b32 v[28:29], v69 offset0:156 offset1:157
	ds_read2st64_b32 v[30:31], v70 offset0:158 offset1:159
	s_waitcnt lgkmcnt(14)
	v_add_f32_e32 v0, v32, v0
	v_mul_f32_e32 v32, v40, v47
	v_fmac_f32_e32 v32, v41, v46
	v_add_f32_e32 v1, v32, v1
	v_mul_f32_e32 v32, v41, v1
	v_mul_f32_e32 v1, v40, v1
	v_fmac_f32_e32 v1, v41, v0
	v_fma_f32 v32, v40, v0, -v32
	v_add_f32_e32 v0, v3, v1
	v_add_f32_e32 v2, v2, v32
	v_mul_f32_e32 v1, v41, v0
	v_fma_f32 v1, v40, v2, -v1
	v_mul_f32_e32 v2, v41, v2
	v_fmac_f32_e32 v2, v40, v0
	s_waitcnt lgkmcnt(13)
	v_add_f32_e32 v0, v5, v2
	v_add_f32_e32 v1, v4, v1
	v_mul_f32_e32 v2, v41, v0
	v_fma_f32 v2, v40, v1, -v2
	v_mul_f32_e32 v1, v41, v1
	v_fmac_f32_e32 v1, v40, v0
	s_waitcnt lgkmcnt(12)
	v_add_f32_e32 v0, v7, v1
	v_add_f32_e32 v2, v6, v2
	v_mul_f32_e32 v1, v41, v0
	v_fma_f32 v1, v40, v2, -v1
	v_mul_f32_e32 v2, v41, v2
	v_fmac_f32_e32 v2, v40, v0
	s_waitcnt lgkmcnt(11)
	v_add_f32_e32 v0, v9, v2
	v_add_f32_e32 v1, v8, v1
	v_mul_f32_e32 v2, v41, v0
	v_fma_f32 v2, v40, v1, -v2
	v_mul_f32_e32 v1, v41, v1
	v_fmac_f32_e32 v1, v40, v0
	s_waitcnt lgkmcnt(10)
	v_add_f32_e32 v0, v11, v1
	v_add_f32_e32 v2, v10, v2
	v_mul_f32_e32 v1, v41, v0
	v_fma_f32 v1, v40, v2, -v1
	v_mul_f32_e32 v2, v41, v2
	v_fmac_f32_e32 v2, v40, v0
	s_waitcnt lgkmcnt(9)
	v_add_f32_e32 v0, v13, v2
	v_add_f32_e32 v1, v12, v1
	v_mul_f32_e32 v2, v41, v0
	v_fma_f32 v2, v40, v1, -v2
	v_mul_f32_e32 v1, v41, v1
	v_fmac_f32_e32 v1, v40, v0
	s_waitcnt lgkmcnt(8)
	v_add_f32_e32 v0, v15, v1
	v_add_f32_e32 v2, v14, v2
	v_mul_f32_e32 v1, v41, v0
	v_fma_f32 v1, v40, v2, -v1
	v_mul_f32_e32 v2, v41, v2
	v_fmac_f32_e32 v2, v40, v0
	s_waitcnt lgkmcnt(7)
	v_add_f32_e32 v0, v17, v2
	v_add_f32_e32 v1, v16, v1
	v_mul_f32_e32 v2, v41, v0
	v_fma_f32 v2, v40, v1, -v2
	v_mul_f32_e32 v1, v41, v1
	v_fmac_f32_e32 v1, v40, v0
	s_waitcnt lgkmcnt(6)
	v_add_f32_e32 v0, v19, v1
	v_add_f32_e32 v2, v18, v2
	v_mul_f32_e32 v1, v41, v0
	v_fma_f32 v1, v40, v2, -v1
	v_mul_f32_e32 v2, v41, v2
	v_fmac_f32_e32 v2, v40, v0
	s_waitcnt lgkmcnt(5)
	v_add_f32_e32 v0, v21, v2
	v_add_f32_e32 v1, v20, v1
	v_mul_f32_e32 v2, v41, v0
	v_fma_f32 v2, v40, v1, -v2
	v_mul_f32_e32 v1, v41, v1
	v_fmac_f32_e32 v1, v40, v0
	s_waitcnt lgkmcnt(4)
	v_add_f32_e32 v0, v23, v1
	v_add_f32_e32 v2, v22, v2
	v_mul_f32_e32 v1, v41, v0
	v_fma_f32 v1, v40, v2, -v1
	v_mul_f32_e32 v2, v41, v2
	v_fmac_f32_e32 v2, v40, v0
	s_waitcnt lgkmcnt(3)
	v_add_f32_e32 v0, v25, v2
	v_add_f32_e32 v1, v24, v1
	v_mul_f32_e32 v2, v41, v0
	v_fma_f32 v2, v40, v1, -v2
	v_mul_f32_e32 v1, v41, v1
	v_fmac_f32_e32 v1, v40, v0
	s_waitcnt lgkmcnt(2)
	v_add_f32_e32 v0, v27, v1
	v_add_f32_e32 v2, v26, v2
	v_mul_f32_e32 v1, v41, v0
	v_fma_f32 v1, v40, v2, -v1
	v_mul_f32_e32 v2, v41, v2
	v_fmac_f32_e32 v2, v40, v0
	s_waitcnt lgkmcnt(1)
	v_add_f32_e32 v0, v29, v2
	v_add_f32_e32 v1, v28, v1
	v_mul_f32_e32 v2, v41, v0
	s_waitcnt lgkmcnt(0)
	v_fma_f32 v2, v40, v1, -v2
	v_mul_f32_e32 v1, v41, v1
	v_fmac_f32_e32 v1, v40, v0
	s_waitcnt lgkmcnt(0)
	v_add_f32_e32 v2, v30, v2
	v_add_f32_e32 v0, v31, v1
	global_store_dword v54, v2, s[14:15]
	global_store_dword v54, v0, s[14:15] offset:256
	s_cbranch_scc0 .LBB0_487

; __global__ void __launch_bounds__(NTHREADS, 2) mega_fwd(Args a) {
	.amdhsa_kernel _Z8mega_fwd4Args
		.amdhsa_group_segment_fixed_size 0
		.amdhsa_private_segment_fixed_size 0
		.amdhsa_kernarg_size 480
		.amdhsa_user_sgpr_count 2
		.amdhsa_user_sgpr_dispatch_ptr 0
		.amdhsa_user_sgpr_queue_ptr 0
		.amdhsa_user_sgpr_kernarg_segment_ptr 1
		.amdhsa_user_sgpr_dispatch_id 0
		.amdhsa_user_sgpr_kernarg_preload_length 0
		.amdhsa_user_sgpr_kernarg_preload_offset 0
		.amdhsa_user_sgpr_private_segment_size 0
		.amdhsa_uses_dynamic_stack 0
		.amdhsa_enable_private_segment 0
		.amdhsa_system_sgpr_workgroup_id_x 1
		.amdhsa_system_sgpr_workgroup_id_y 0
		.amdhsa_system_sgpr_workgroup_id_z 0
		.amdhsa_system_sgpr_workgroup_info 0
		.amdhsa_system_vgpr_workitem_id 2
		.amdhsa_next_free_vgpr 250
		.amdhsa_next_free_sgpr 102
		.amdhsa_accum_offset 252
		.amdhsa_reserve_vcc 1
		.amdhsa_float_round_mode_32 0
		.amdhsa_float_round_mode_16_64 0
		.amdhsa_float_denorm_mode_32 3
		.amdhsa_float_denorm_mode_16_64 3
		.amdhsa_dx10_clamp 1
		.amdhsa_ieee_mode 1
		.amdhsa_fp16_overflow 0
		.amdhsa_tg_split 0
		.amdhsa_exception_fp_ieee_invalid_op 0
		.amdhsa_exception_fp_denorm_src 0
		.amdhsa_exception_fp_ieee_div_zero 0
		.amdhsa_exception_fp_ieee_overflow 0
		.amdhsa_exception_fp_ieee_underflow 0
		.amdhsa_exception_fp_ieee_inexact 0
		.amdhsa_exception_int_div_zero 0
	.end_amdhsa_kernel

; __global__ void __launch_bounds__(NTHREADS, 2) mega_fwd(Args a) {
amdhsa.kernels:
  - .agpr_count:     0
    .args:
      - .offset:         0
        .size:           224
        .value_kind:     by_value
      - .offset:         224
        .size:           4
        .value_kind:     hidden_block_count_x
      - .offset:         228
        .size:           4
        .value_kind:     hidden_block_count_y
      - .offset:         232
        .size:           4
        .value_kind:     hidden_block_count_z
      - .offset:         236
        .size:           2
        .value_kind:     hidden_group_size_x
      - .offset:         238
        .size:           2
        .value_kind:     hidden_group_size_y
      - .offset:         240
        .size:           2
        .value_kind:     hidden_group_size_z
      - .offset:         242
        .size:           2
        .value_kind:     hidden_remainder_x
      - .offset:         244
        .size:           2
        .value_kind:     hidden_remainder_y
      - .offset:         246
        .size:           2
        .value_kind:     hidden_remainder_z
      - .offset:         264
        .size:           8
        .value_kind:     hidden_global_offset_x
      - .offset:         272
        .size:           8
        .value_kind:     hidden_global_offset_y
      - .offset:         280
        .size:           8
        .value_kind:     hidden_global_offset_z
      - .offset:         288
        .size:           2
        .value_kind:     hidden_grid_dims
      - .offset:         312
        .size:           8
        .value_kind:     hidden_multigrid_sync_arg
      - .offset:         344
        .size:           4
        .value_kind:     hidden_dynamic_lds_size
    .group_segment_fixed_size: 0
    .kernarg_segment_align: 8
    .kernarg_segment_size: 480
    .language:       OpenCL C
    .language_version:
      - 2
      - 0
    .max_flat_workgroup_size: 512
    .name:           _Z8mega_fwd4Args
    .private_segment_fixed_size: 0
    .sgpr_count:     108
    .sgpr_spill_count: 40
    .symbol:         _Z8mega_fwd4Args.kd
    .uniform_work_group_size: 1
    .uses_dynamic_stack: false
    .vgpr_count:     250
    .vgpr_spill_count: 0
    .wavefront_size: 64
